# phase 1 DFT fold loop: twiddles fetched with one per-lane LDS read and broadcast by v_readlane into SGPR-pair packed operands (replaces 32 broadcast reads + ~85 scalar ops per 4 columns; same FMA orde
# speedup vs baseline: 1.0082x; 1.0082x over previous
.LBB0_79:
	s_or_b64 exec, exec, s[6:7]
	s_and_b32 s6, s2, 3
	s_movk_i32 s23, 0x404
	v_mad_u32_u24 v13, v102, s23, 0
	s_lshl_b32 s23, s6, 7
	s_lshl_b32 s29, s3, 4
	s_mul_i32 s40, s6, 0x60
	s_mul_i32 s41, s3, 12
	s_lshl_b32 s7, s3, 2
	s_lshl_b32 s22, s6, 5
	s_add_i32 s23, s23, s29
	s_add_i32 s40, s40, s41
	s_lshl_b32 s41, s6, 6
	s_lshl_b32 s42, s3, 3
	v_mov_b32_e32 v12, 0
	s_add_i32 s7, s7, s22
	s_mov_b32 s22, 0
	s_or_b32 s29, s23, 4
	s_or_b32 s30, s23, 8
	s_or_b32 s31, s23, 12
	s_add_i32 s41, s41, s42
	s_add_i32 s42, 0, 0x10100
	s_add_i32 s43, 0, 0x10500
	s_mov_b32 s45, 0
	s_mov_b32 s46, 0
	s_mov_b32 s47, 0
	s_mov_b32 s48, 0
	v_mov_b32_e32 v6, 0
	v_mov_b32_e32 v7, v12
	v_mov_b32_e32 v2, 0
	v_mov_b32_e32 v3, v12
	v_mov_b32_e32 v4, 0
	v_mov_b32_e32 v5, v12
	v_mov_b32_e32 v0, 0
	v_mov_b32_e32 v1, v12
	s_waitcnt lgkmcnt(0)
	s_barrier
	v_and_b32_e32 v50, 3, v102
	v_add_u32_e32 v51, s7, v50
	v_lshlrev_b32_e32 v52, 2, v51
	v_bfe_u32 v53, v102, 3, 2
	v_mul_u32_u24_e32 v54, v51, v53
	v_bfe_u32 v55, v102, 2, 1
	v_lshl_add_u32 v55, v55, 10, s42
.LBB0_80:
	ds_read2_b32 v[8:9], v13 offset1:1
	ds_read2_b32 v[10:11], v13 offset0:2 offset1:3
	v_and_b32_e32 v56, 0xff, v54
	v_lshl_add_u32 v56, v56, 2, v55
	ds_read_b32 v57, v56
	v_add_u32_e32 v54, v54, v52
	v_add_u32_e32 v13, 16, v13
	s_add_i32 s48, s48, 4
	s_waitcnt lgkmcnt(0)
	v_readlane_b32 s64, v57, 0
	v_readlane_b32 s65, v57, 1
	v_readlane_b32 s66, v57, 2
	v_readlane_b32 s67, v57, 3
	v_readlane_b32 s68, v57, 4
	v_readlane_b32 s69, v57, 5
	v_readlane_b32 s70, v57, 6
	v_readlane_b32 s71, v57, 7
	v_readlane_b32 s72, v57, 8
	v_readlane_b32 s73, v57, 9
	v_readlane_b32 s74, v57, 10
	v_readlane_b32 s75, v57, 11
	v_readlane_b32 s76, v57, 12
	v_readlane_b32 s77, v57, 13
	v_readlane_b32 s78, v57, 14
	v_readlane_b32 s79, v57, 15
	v_readlane_b32 s80, v57, 16
	v_readlane_b32 s81, v57, 17
	v_readlane_b32 s82, v57, 18
	v_readlane_b32 s83, v57, 19
	v_readlane_b32 s84, v57, 20
	v_readlane_b32 s85, v57, 21
	v_readlane_b32 s86, v57, 22
	v_readlane_b32 s87, v57, 23
	v_readlane_b32 s88, v57, 24
	v_readlane_b32 s89, v57, 25
	v_readlane_b32 s90, v57, 26
	v_readlane_b32 s91, v57, 27
	v_readlane_b32 s92, v57, 28
	v_readlane_b32 s93, v57, 29
	v_readlane_b32 s94, v57, 30
	v_readlane_b32 s95, v57, 31
	s_cmpk_eq_i32 s48, 0x100
	v_add_f32_e32 v12, v12, v8
	v_pk_fma_f32 v[6:7], v[8:9], s[64:65], v[6:7] op_sel_hi:[0,1,1]
	v_pk_fma_f32 v[4:5], v[8:9], s[68:69], v[4:5] op_sel_hi:[0,1,1] neg_lo:[1,0,0] neg_hi:[1,0,0]
	v_pk_fma_f32 v[2:3], v[8:9], s[66:67], v[2:3] op_sel_hi:[0,1,1]
	v_pk_fma_f32 v[0:1], v[8:9], s[70:71], v[0:1] op_sel_hi:[0,1,1] neg_lo:[1,0,0] neg_hi:[1,0,0]
	v_sub_f32_e32 v12, v12, v9
	v_pk_fma_f32 v[6:7], v[8:9], s[72:73], v[6:7] op_sel:[1,0,0]
	v_pk_fma_f32 v[4:5], v[8:9], s[76:77], v[4:5] op_sel:[1,0,0] neg_lo:[1,0,0] neg_hi:[1,0,0]
	v_pk_fma_f32 v[2:3], v[8:9], s[74:75], v[2:3] op_sel:[1,0,0]
	v_pk_fma_f32 v[0:1], v[8:9], s[78:79], v[0:1] op_sel:[1,0,0] neg_lo:[1,0,0] neg_hi:[1,0,0]
	v_add_f32_e32 v12, v12, v10
	v_pk_fma_f32 v[6:7], v[10:11], s[80:81], v[6:7] op_sel_hi:[0,1,1]
	v_pk_fma_f32 v[4:5], v[10:11], s[84:85], v[4:5] op_sel_hi:[0,1,1] neg_lo:[1,0,0] neg_hi:[1,0,0]
	v_pk_fma_f32 v[2:3], v[10:11], s[82:83], v[2:3] op_sel_hi:[0,1,1]
	v_pk_fma_f32 v[0:1], v[10:11], s[86:87], v[0:1] op_sel_hi:[0,1,1] neg_lo:[1,0,0] neg_hi:[1,0,0]
	v_sub_f32_e32 v12, v12, v11
	v_pk_fma_f32 v[6:7], v[10:11], s[88:89], v[6:7] op_sel:[1,0,0]
	v_pk_fma_f32 v[4:5], v[10:11], s[92:93], v[4:5] op_sel:[1,0,0] neg_lo:[1,0,0] neg_hi:[1,0,0]
	v_pk_fma_f32 v[2:3], v[10:11], s[90:91], v[2:3] op_sel:[1,0,0]
	v_pk_fma_f32 v[0:1], v[10:11], s[94:95], v[0:1] op_sel:[1,0,0] neg_lo:[1,0,0] neg_hi:[1,0,0]
	s_cbranch_scc0 .LBB0_80
	s_lshl_b32 s5, s5, 7
	s_add_i32 s22, s7, s5
	s_ashr_i32 s5, s4, 31
	s_lshl_b64 s[30:31], s[4:5], 1
	s_add_u32 s30, s38, s30
	v_mov_b32_e32 v9, 0
	s_addc_u32 s31, s39, s31
	v_lshlrev_b32_e32 v8, 1, v102
	s_mov_b32 s23, 0
	v_lshl_add_u64 v[8:9], s[30:31], 0, v[8:9]
	s_mov_b64 s[30:31], 0x1200000
	v_lshl_add_u64 v[8:9], v[8:9], 0, s[30:31]
	v_bfe_u32 v10, v6, 16, 1
	s_movk_i32 s5, 0x7fff
	s_lshl_b64 s[30:31], s[22:23], 11
	v_add3_u32 v6, v6, v10, s5
	v_lshl_add_u64 v[10:11], v[8:9], 0, s[30:31]
	s_add_i32 s30, s22, 0x200
	s_mov_b32 s31, s23
	global_store_short_d16_hi v[10:11], v6, off
	v_bfe_u32 v6, v4, 16, 1
	s_lshl_b64 s[30:31], s[30:31], 11
	v_add3_u32 v4, v4, v6, s5
	v_lshl_add_u64 v[10:11], v[8:9], 0, s[30:31]
	s_or_b32 s30, s22, 1
	s_mov_b32 s31, s23
	global_store_short_d16_hi v[10:11], v4, off
	v_bfe_u32 v4, v7, 16, 1
	s_lshl_b64 s[30:31], s[30:31], 11
	v_add3_u32 v4, v7, v4, s5
	v_lshl_add_u64 v[6:7], v[8:9], 0, s[30:31]
	s_add_i32 s30, s22, 0x201
	s_mov_b32 s31, s23
	global_store_short_d16_hi v[6:7], v4, off
	v_bfe_u32 v4, v5, 16, 1
	s_lshl_b64 s[30:31], s[30:31], 11
	v_add3_u32 v6, v5, v4, s5
	v_lshl_add_u64 v[4:5], v[8:9], 0, s[30:31]
	s_or_b32 s30, s22, 2
	s_mov_b32 s31, s23
	global_store_short_d16_hi v[4:5], v6, off
	v_bfe_u32 v4, v2, 16, 1
	s_lshl_b64 s[30:31], s[30:31], 11
	v_add3_u32 v2, v2, v4, s5
	v_lshl_add_u64 v[4:5], v[8:9], 0, s[30:31]
	s_add_i32 s30, s22, 0x202
	s_mov_b32 s31, s23
	global_store_short_d16_hi v[4:5], v2, off
	v_bfe_u32 v2, v0, 16, 1
	s_lshl_b64 s[30:31], s[30:31], 11
	v_add3_u32 v0, v0, v2, s5
	v_lshl_add_u64 v[4:5], v[8:9], 0, s[30:31]
	s_or_b32 s30, s22, 3
	s_mov_b32 s31, s23
	global_store_short_d16_hi v[4:5], v0, off
	v_bfe_u32 v0, v3, 16, 1
	s_lshl_b64 s[30:31], s[30:31], 11
	v_add3_u32 v0, v3, v0, s5
	v_lshl_add_u64 v[2:3], v[8:9], 0, s[30:31]
	global_store_short_d16_hi v[2:3], v0, off
	v_bfe_u32 v0, v1, 16, 1
	s_addk_i32 s22, 0x203
	v_add3_u32 v2, v1, v0, s5
	s_lshl_b64 s[22:23], s[22:23], 11
	s_or_b32 s5, s3, s6
	v_lshl_add_u64 v[0:1], v[8:9], 0, s[22:23]
	s_cmp_eq_u32 s5, 0
	global_store_short_d16_hi v[0:1], v2, off
	s_cbranch_scc0 .LBB0_83
	s_add_i32 s28, s28, s4
	v_or_b32_e32 v0, s28, v102
	v_ashrrev_i32_e32 v1, 31, v0
	v_lshl_add_u64 v[0:1], v[0:1], 2, s[38:39]
	v_add_co_u32_e32 v0, vcc, 0x15e0000, v0
	v_mul_f32_e32 v2, 0x3d800000, v12
	s_nop 0
	v_addc_co_u32_e32 v1, vcc, 0, v1, vcc
	global_store_dword v[0:1], v2, off
